# half-tile last round with reduced K-loop plus attention QK operand reads issued two k-steps ahead
# speedup vs baseline: 1.0135x; 1.0135x over previous
; #define LAS __attribute__((address_space(3)))
; __device__ __forceinline__ void attn_unit(LAS unsigned char* lds, const bf16* __restrict__ proj, bf16* __restrict__ mix, int b, int h, int qb, float lam, float sl2,
;                                           const float* __restrict__ sg, float oscale, const int tid_in) {
;     ...
;             float base = sl2 * (float)(kt * 64 + 4 * hi - qpos) - mref; asm volatile("" : "+v"(base));
; #pragma unroll
;             for (int r = 0; r < 16; ++r) { p0[r] = __builtin_fmaf(sl2, (float)((r & 3) + 8 * (r >> 2)), base); p1[r] = __builtin_fmaf(sl2, (float)((r & 3) + 8 * (r >> 2) + 32), base); }
; #pragma unroll
;             for (int d0 = 0; d0 < 4; ++d0) { const bf16x8 k0 = *(LAS const bf16x8*)(kc + d0 * 32), k1 = *(LAS const bf16x8*)(kc + 32 * KSTR + d0 * 32), qv = *(LAS const bf16x8*)(qs + d0 * 32);
;                 p0 = __builtin_amdgcn_mfma_f32_32x32x16_bf16(k0, qv, p0, 0, 0, 0); p1 = __builtin_amdgcn_mfma_f32_32x32x16_bf16(k1, qv, p1, 0, 0, 0); }
.LBB0_189:
	s_bitcmp1_b32 s0, 0
	v_add_u32_e32 v64, s12, v153
	v_cvt_f32_i32_e32 v64, v64
	s_cselect_b32 s0, 0x9800, 0
	s_add_i32 s16, s0, 0
	s_mul_i32 s0, s10, 0x2400
	s_add_i32 s0, s16, s0
	v_add3_u32 v204, s0, v141, v124
	s_mov_b32 s0, 0x41800000
	v_fma_f32 v84, v154, v64, -v202
	s_mov_b32 s1, 0x41880000
	v_mov_b32_e32 v155, v154
	v_pk_fma_f32 v[94:95], v[156:157], s[0:1], v[84:85] op_sel_hi:[1,1,0]
	s_mov_b32 s0, 0x41900000
	s_mov_b32 s1, 0x41980000
	v_pk_fma_f32 v[96:97], v[156:157], s[0:1], v[84:85] op_sel_hi:[1,1,0]
	s_mov_b32 s0, 0x41c00000
	s_mov_b32 s1, 0x41c80000
	v_pk_fma_f32 v[98:99], v[156:157], s[0:1], v[84:85] op_sel_hi:[1,1,0]
	s_mov_b32 s0, 0x41d00000
	s_mov_b32 s1, 0x41d80000
	v_pk_fma_f32 v[100:101], v[156:157], s[0:1], v[84:85] op_sel_hi:[1,1,0]
	s_mov_b32 s0, 0x42680000
	s_mov_b32 s1, 0x426c0000
	v_pk_fma_f32 v[78:79], v[154:155], s[0:1], v[84:85] op_sel_hi:[1,1,0]
	s_mov_b32 s0, 0x42600000
	s_mov_b32 s1, 0x42640000
	v_pk_fma_f32 v[76:77], v[154:155], s[0:1], v[84:85] op_sel_hi:[1,1,0]
	s_mov_b32 s0, 0x42480000
	ds_read_b128 v[64:67], v204
	ds_read_b128 v[226:229], v149
	s_mov_b32 s1, 0x424c0000
	v_pk_fma_f32 v[74:75], v[154:155], s[0:1], v[84:85] op_sel_hi:[1,1,0]
	s_mov_b32 s0, 0x42400000
	s_mov_b32 s1, 0x42440000
	ds_read_b128 v[230:233], v204 offset:4608
	v_pk_fma_f32 v[72:73], v[154:155], s[0:1], v[84:85] op_sel_hi:[1,1,0]
	s_mov_b32 s0, 0x42280000
	s_mov_b32 s36, 2.0
	s_mov_b32 s1, 0x422c0000
	s_mov_b32 s37, 0x40400000
	v_pk_fma_f32 v[70:71], v[154:155], s[0:1], v[84:85] op_sel_hi:[1,1,0]
	s_mov_b32 s0, 0x42200000
	v_pk_fma_f32 v[88:89], v[156:157], s[36:37], v[84:85] op_sel_hi:[1,1,0]
	s_mov_b32 s36, 0x41200000
	s_mov_b32 s1, 0x42240000
	s_mov_b32 s37, 0x41300000
	v_pk_fma_f32 v[68:69], v[154:155], s[0:1], v[84:85] op_sel_hi:[1,1,0]
	s_mov_b32 s0, 0x42080000
	v_fma_f32 v86, 0, v154, v84
	v_add_f32_e32 v87, v154, v84
	v_pk_fma_f32 v[90:91], v[156:157], s[82:83], v[84:85] op_sel_hi:[1,1,0]
	v_pk_fma_f32 v[92:93], v[156:157], s[36:37], v[84:85] op_sel_hi:[1,1,0]
	s_mov_b32 s1, 0x420c0000
	ds_read_b128 v[234:237], v204 offset:32
	ds_read_b128 v[238:241], v149 offset:32
	ds_read_b128 v[242:245], v204 offset:4640
	s_waitcnt lgkmcnt(4)
	v_mfma_f32_32x32x16_bf16 v[86:101], v[64:67], v[226:229], v[86:101]
	v_fma_f32 v66, v154, s0, v84
	v_fma_f32 v67, v155, s1, v84
	s_mov_b32 s0, 0x42000000
	s_mov_b32 s1, 0x42040000
	v_fma_f32 v64, v158, s0, v84
	v_fma_f32 v65, v159, s1, v84
	s_add_i32 s0, s12, 63
	s_cmp_le_u32 s0, s11
	s_waitcnt lgkmcnt(3)
	v_mfma_f32_32x32x16_bf16 v[64:79], v[230:233], v[226:229], v[64:79]
	ds_read_b128 v[246:249], v204 offset:64
	ds_read_b128 v[226:229], v149 offset:64
	ds_read_b128 v[230:233], v204 offset:4672
	s_waitcnt lgkmcnt(4)
	v_mfma_f32_32x32x16_bf16 v[86:101], v[234:237], v[238:241], v[86:101]
	s_waitcnt lgkmcnt(3)
	v_mfma_f32_32x32x16_bf16 v[64:79], v[242:245], v[238:241], v[64:79]
	ds_read_b128 v[234:237], v204 offset:96
	ds_read_b128 v[238:241], v149 offset:96
	ds_read_b128 v[242:245], v204 offset:4704
	s_waitcnt lgkmcnt(4)
	v_mfma_f32_32x32x16_bf16 v[86:101], v[246:249], v[226:229], v[86:101]
	s_waitcnt lgkmcnt(3)
	v_mfma_f32_32x32x16_bf16 v[64:79], v[230:233], v[226:229], v[64:79]
	s_waitcnt lgkmcnt(1)
	v_mfma_f32_32x32x16_bf16 v[86:101], v[234:237], v[238:241], v[86:101]
	s_waitcnt lgkmcnt(0)
	v_mfma_f32_32x32x16_bf16 v[64:79], v[242:245], v[238:241], v[64:79]
	s_cbranch_scc1 .LBB0_191
; __device__ __forceinline__ void attn_unit(LAS unsigned char* lds, const bf16* __restrict__ proj, bf16* __restrict__ mix, int b, int h, int qb, float lam, float sl2,
;                                           const float* __restrict__ sg, float oscale, const int tid_in) {
;     ...
;             if (kt * 64 + 63 > q0) { const int dqi = qpos - kt * 64 - 4 * hi;
; #pragma unroll
;                 for (int r = 0; r < 16; ++r) { if ((r & 3) + 8 * (r >> 2) > dqi) p0[r] = -INFINITY; if ((r & 3) + 8 * (r >> 2) + 32 > dqi) p1[r] = -INFINITY; } }
	v_cmp_gt_i32_e64 s[94:95], 26, v151
	v_cmp_gt_i32_e64 s[96:97], 27, v151
	v_cmp_gt_i32_e64 s[92:93], 25, v151
	s_and_b64 s[94:95], s[96:97], s[94:95]
	v_cmp_gt_i32_e64 s[90:91], 24, v151
	s_and_b64 s[92:93], s[94:95], s[92:93]
	v_cmp_gt_i32_e64 s[88:89], 19, v151
	s_and_b64 s[90:91], s[92:93], s[90:91]
	v_cmp_gt_i32_e64 s[86:87], 18, v151
	s_and_b64 s[88:89], s[90:91], s[88:89]
	v_cmp_gt_i32_e64 s[84:85], 17, v151
	s_and_b64 s[86:87], s[88:89], s[86:87]
	v_cmp_gt_i32_e64 s[80:81], 16, v151
	s_and_b64 s[84:85], s[86:87], s[84:85]
	v_cmp_gt_i32_e64 s[78:79], 11, v151
	s_and_b64 s[80:81], s[84:85], s[80:81]
	v_cmp_gt_i32_e64 s[76:77], 10, v151
	s_and_b64 s[78:79], s[80:81], s[78:79]
	v_cmp_gt_i32_e64 s[74:75], 9, v151
	s_and_b64 s[76:77], s[78:79], s[76:77]
	v_cmp_gt_i32_e64 s[72:73], 8, v151
	s_and_b64 s[74:75], s[76:77], s[74:75]
	v_cmp_gt_i32_e64 s[70:71], 3, v151
	s_and_b64 s[72:73], s[74:75], s[72:73]
	v_cmp_gt_i32_e64 s[68:69], 2, v151
	s_and_b64 s[70:71], s[72:73], s[70:71]
	v_cmp_gt_i32_e64 s[66:67], 1, v151
	s_and_b64 s[68:69], s[70:71], s[68:69]
	v_cmp_gt_i32_e64 s[64:65], 0, v151
	s_and_b64 s[66:67], s[68:69], s[66:67]
	s_and_b64 s[64:65], s[66:67], s[64:65]
	v_cmp_gt_i32_e64 s[62:63], 58, v151
	v_cndmask_b32_e64 v86, v86, v221, s[64:65]
	v_cmp_gt_i32_e64 s[64:65], 59, v151
	v_cmp_gt_i32_e64 s[60:61], 57, v151
	s_and_b64 s[62:63], s[64:65], s[62:63]
	v_cmp_gt_i32_e64 s[58:59], 56, v151
	s_and_b64 s[60:61], s[62:63], s[60:61]
	v_cmp_gt_i32_e64 s[56:57], 51, v151
	s_and_b64 s[58:59], s[60:61], s[58:59]
	v_cmp_gt_i32_e64 s[54:55], 50, v151
	s_and_b64 s[56:57], s[58:59], s[56:57]
	v_cmp_gt_i32_e64 s[50:51], 49, v151
	s_and_b64 s[54:55], s[56:57], s[54:55]
	v_cmp_gt_i32_e64 s[48:49], 48, v151
	s_and_b64 s[50:51], s[54:55], s[50:51]
	v_cmp_gt_i32_e64 s[46:47], 43, v151
	s_and_b64 s[48:49], s[50:51], s[48:49]
	v_cmp_gt_i32_e64 s[44:45], 42, v151
	s_and_b64 s[46:47], s[48:49], s[46:47]
	v_cmp_gt_i32_e64 s[42:43], 41, v151
	s_and_b64 s[44:45], s[46:47], s[44:45]
	v_cmp_gt_i32_e64 s[40:41], 40, v151
	s_and_b64 s[42:43], s[44:45], s[42:43]
	v_cmp_gt_i32_e64 s[38:39], 35, v151
	s_and_b64 s[40:41], s[42:43], s[40:41]
	v_cmp_gt_i32_e64 s[36:37], 34, v151
	s_and_b64 s[38:39], s[40:41], s[38:39]
	v_cmp_gt_i32_e64 s[0:1], 33, v151
	s_and_b64 s[36:37], s[38:39], s[36:37]
	v_cmp_gt_i32_e32 vcc, 32, v151
	s_and_b64 s[0:1], s[36:37], s[0:1]
	v_cndmask_b32_e64 v88, v88, v221, s[68:69]
	v_readlane_b32 s68, v255, 2
	s_and_b64 vcc, s[0:1], vcc
	v_cndmask_b32_e64 v101, v101, v221, s[96:97]
	v_cndmask_b32_e64 v100, v100, v221, s[94:95]
	v_cndmask_b32_e64 v99, v99, v221, s[92:93]
	v_cndmask_b32_e64 v98, v98, v221, s[90:91]
	v_cndmask_b32_e64 v97, v97, v221, s[88:89]
	v_cndmask_b32_e64 v96, v96, v221, s[86:87]
	v_cndmask_b32_e64 v95, v95, v221, s[84:85]
	v_cndmask_b32_e64 v94, v94, v221, s[80:81]
	v_cndmask_b32_e64 v93, v93, v221, s[78:79]
	v_cndmask_b32_e64 v92, v92, v221, s[76:77]
	v_cndmask_b32_e64 v91, v91, v221, s[74:75]
	v_cndmask_b32_e64 v90, v90, v221, s[72:73]
	s_mov_b32 s72, s18
	v_cndmask_b32_e64 v89, v89, v221, s[70:71]
	v_readlane_b32 s71, v255, 13
	v_readlane_b32 s19, v255, 12
	v_readlane_b32 s70, v255, 11
	v_readlane_b32 s69, v255, 3
	v_cndmask_b32_e64 v87, v87, v221, s[66:67]
	v_cndmask_b32_e64 v79, v79, v221, s[64:65]
	v_cndmask_b32_e64 v78, v78, v221, s[62:63]
	s_mov_b32 s62, s26
	v_cndmask_b32_e64 v77, v77, v221, s[60:61]
	v_cndmask_b32_e64 v76, v76, v221, s[58:59]
	v_cndmask_b32_e64 v75, v75, v221, s[56:57]
	v_cndmask_b32_e64 v74, v74, v221, s[54:55]
	v_cndmask_b32_e64 v73, v73, v221, s[50:51]
	v_cndmask_b32_e64 v72, v72, v221, s[48:49]
	v_cndmask_b32_e64 v71, v71, v221, s[46:47]
	v_cndmask_b32_e64 v70, v70, v221, s[44:45]
	v_cndmask_b32_e64 v69, v69, v221, s[42:43]
	v_cndmask_b32_e64 v68, v68, v221, s[40:41]
	v_cndmask_b32_e64 v67, v67, v221, s[38:39]
	v_cndmask_b32_e64 v66, v66, v221, s[36:37]
	v_cndmask_b32_e64 v65, v65, v221, s[0:1]
	v_cndmask_b32_e32 v64, v64, v221, vcc

; #define LAS __attribute__((address_space(3)))
; __device__ __forceinline__ void attn_unit(LAS unsigned char* lds, const bf16* __restrict__ proj, bf16* __restrict__ mix, int b, int h, int qb, float lam, float sl2,
;                                           const float* __restrict__ sg, float oscale, const int tid_in) {
;     ...
;             float base = sl2 * (float)(kt * 64 + 4 * hi - qpos) - mref; asm volatile("" : "+v"(base));
; #pragma unroll
;             for (int r = 0; r < 16; ++r) { p0[r] = __builtin_fmaf(sl2, (float)((r & 3) + 8 * (r >> 2)), base); p1[r] = __builtin_fmaf(sl2, (float)((r & 3) + 8 * (r >> 2) + 32), base); }
; #pragma unroll
;             for (int d0 = 0; d0 < 4; ++d0) { const bf16x8 k0 = *(LAS const bf16x8*)(kc + d0 * 32), k1 = *(LAS const bf16x8*)(kc + 32 * KSTR + d0 * 32), qv = *(LAS const bf16x8*)(qs + d0 * 32);
;                 p0 = __builtin_amdgcn_mfma_f32_32x32x16_bf16(k0, qv, p0, 0, 0, 0); p1 = __builtin_amdgcn_mfma_f32_32x32x16_bf16(k1, qv, p1, 0, 0, 0); }
.LBB0_206:
	s_bitcmp1_b32 s0, 0
	v_add_u32_e32 v64, s6, v153
	v_cvt_f32_i32_e32 v64, v64
	s_cselect_b32 s0, 0x9800, 0
	s_add_i32 s13, s0, 0
	s_mul_i32 s0, s8, 0x2400
	s_add_i32 s0, s13, s0
	v_add3_u32 v216, s0, v141, v124
	s_mov_b32 s0, 0x41800000
	v_fma_f32 v84, v154, v64, -v164
	s_mov_b32 s1, 0x41880000
	v_mov_b32_e32 v155, v154
	v_pk_fma_f32 v[94:95], v[156:157], s[0:1], v[84:85] op_sel_hi:[1,1,0]
	s_mov_b32 s0, 0x41900000
	s_mov_b32 s1, 0x41980000
	v_pk_fma_f32 v[96:97], v[156:157], s[0:1], v[84:85] op_sel_hi:[1,1,0]
	s_mov_b32 s0, 0x41c00000
	s_mov_b32 s1, 0x41c80000
	v_pk_fma_f32 v[98:99], v[156:157], s[0:1], v[84:85] op_sel_hi:[1,1,0]
	s_mov_b32 s0, 0x41d00000
	s_mov_b32 s1, 0x41d80000
	v_pk_fma_f32 v[100:101], v[156:157], s[0:1], v[84:85] op_sel_hi:[1,1,0]
	s_mov_b32 s0, 0x42680000
	s_mov_b32 s1, 0x426c0000
	v_pk_fma_f32 v[78:79], v[154:155], s[0:1], v[84:85] op_sel_hi:[1,1,0]
	s_mov_b32 s0, 0x42600000
	s_mov_b32 s1, 0x42640000
	v_pk_fma_f32 v[76:77], v[154:155], s[0:1], v[84:85] op_sel_hi:[1,1,0]
	s_mov_b32 s0, 0x42480000
	ds_read_b128 v[64:67], v216
	ds_read_b128 v[166:169], v149
	s_mov_b32 s1, 0x424c0000
	v_pk_fma_f32 v[74:75], v[154:155], s[0:1], v[84:85] op_sel_hi:[1,1,0]
	s_mov_b32 s0, 0x42400000
	s_mov_b32 s1, 0x42440000
	ds_read_b128 v[202:205], v216 offset:4608
	v_pk_fma_f32 v[72:73], v[154:155], s[0:1], v[84:85] op_sel_hi:[1,1,0]
	s_mov_b32 s0, 0x42280000
	s_mov_b32 s14, 2.0
	s_mov_b32 s1, 0x422c0000
	s_mov_b32 s15, 0x40400000
	v_pk_fma_f32 v[70:71], v[154:155], s[0:1], v[84:85] op_sel_hi:[1,1,0]
	s_mov_b32 s0, 0x42200000
	v_pk_fma_f32 v[88:89], v[156:157], s[14:15], v[84:85] op_sel_hi:[1,1,0]
	s_mov_b32 s14, 0x41200000
	s_mov_b32 s1, 0x42240000
	s_mov_b32 s15, 0x41300000
	v_pk_fma_f32 v[68:69], v[154:155], s[0:1], v[84:85] op_sel_hi:[1,1,0]
	s_mov_b32 s0, 0x42080000
	v_fma_f32 v86, 0, v154, v84
	v_add_f32_e32 v87, v154, v84
	v_pk_fma_f32 v[90:91], v[156:157], s[82:83], v[84:85] op_sel_hi:[1,1,0]
	v_pk_fma_f32 v[92:93], v[156:157], s[14:15], v[84:85] op_sel_hi:[1,1,0]
	s_mov_b32 s1, 0x420c0000
	ds_read_b128 v[234:237], v216 offset:32
	ds_read_b128 v[238:241], v149 offset:32
	ds_read_b128 v[242:245], v216 offset:4640
	s_waitcnt lgkmcnt(4)
	v_mfma_f32_32x32x16_bf16 v[86:101], v[64:67], v[166:169], v[86:101]
	v_fma_f32 v66, v154, s0, v84
	v_fma_f32 v67, v155, s1, v84
	s_mov_b32 s0, 0x42000000
	s_mov_b32 s1, 0x42040000
	v_fma_f32 v64, v158, s0, v84
	v_fma_f32 v65, v159, s1, v84
	s_add_i32 s0, s6, 63
	s_cmp_le_u32 s0, s9
	s_waitcnt lgkmcnt(3)
	v_mfma_f32_32x32x16_bf16 v[64:79], v[202:205], v[166:169], v[64:79]
	ds_read_b128 v[246:249], v216 offset:64
	ds_read_b128 v[166:169], v149 offset:64
	ds_read_b128 v[202:205], v216 offset:4672
	s_waitcnt lgkmcnt(4)
	v_mfma_f32_32x32x16_bf16 v[86:101], v[234:237], v[238:241], v[86:101]
	s_waitcnt lgkmcnt(3)
	v_mfma_f32_32x32x16_bf16 v[64:79], v[242:245], v[238:241], v[64:79]
	ds_read_b128 v[234:237], v216 offset:96
	ds_read_b128 v[238:241], v149 offset:96
	ds_read_b128 v[242:245], v216 offset:4704
	s_waitcnt lgkmcnt(4)
	v_mfma_f32_32x32x16_bf16 v[86:101], v[246:249], v[166:169], v[86:101]
	s_waitcnt lgkmcnt(3)
	v_mfma_f32_32x32x16_bf16 v[64:79], v[202:205], v[166:169], v[64:79]
	s_waitcnt lgkmcnt(1)
	v_mfma_f32_32x32x16_bf16 v[86:101], v[234:237], v[238:241], v[86:101]
	s_waitcnt lgkmcnt(0)
	v_mfma_f32_32x32x16_bf16 v[64:79], v[242:245], v[238:241], v[64:79]
	s_cbranch_scc1 .LBB0_208
; __device__ __forceinline__ void attn_unit(LAS unsigned char* lds, const bf16* __restrict__ proj, bf16* __restrict__ mix, int b, int h, int qb, float lam, float sl2,
;                                           const float* __restrict__ sg, float oscale, const int tid_in) {
;     ...
;             if (kt * 64 + 63 > q0) { const int dqi = qpos - kt * 64 - 4 * hi;
; #pragma unroll
;                 for (int r = 0; r < 16; ++r) { if ((r & 3) + 8 * (r >> 2) > dqi) p0[r] = -INFINITY; if ((r & 3) + 8 * (r >> 2) + 32 > dqi) p1[r] = -INFINITY; } }
	v_cmp_gt_i32_e64 s[94:95], 26, v151
	v_cmp_gt_i32_e64 s[96:97], 27, v151
	v_cmp_gt_i32_e64 s[92:93], 25, v151
	s_and_b64 s[94:95], s[96:97], s[94:95]
	v_cmp_gt_i32_e64 s[90:91], 24, v151
	s_and_b64 s[92:93], s[94:95], s[92:93]
	v_cmp_gt_i32_e64 s[88:89], 19, v151
	s_and_b64 s[90:91], s[92:93], s[90:91]
	v_cmp_gt_i32_e64 s[86:87], 18, v151
	s_and_b64 s[88:89], s[90:91], s[88:89]
	v_cmp_gt_i32_e64 s[84:85], 17, v151
	s_and_b64 s[86:87], s[88:89], s[86:87]
	v_cmp_gt_i32_e64 s[80:81], 16, v151
	s_and_b64 s[84:85], s[86:87], s[84:85]
	v_cmp_gt_i32_e64 s[78:79], 11, v151
	s_and_b64 s[80:81], s[84:85], s[80:81]
	v_cmp_gt_i32_e64 s[76:77], 10, v151
	s_and_b64 s[78:79], s[80:81], s[78:79]
	v_cmp_gt_i32_e64 s[74:75], 9, v151
	s_and_b64 s[76:77], s[78:79], s[76:77]
	v_cmp_gt_i32_e64 s[72:73], 8, v151
	s_and_b64 s[74:75], s[76:77], s[74:75]
	v_cmp_gt_i32_e64 s[70:71], 3, v151
	s_and_b64 s[72:73], s[74:75], s[72:73]
	v_cmp_gt_i32_e64 s[68:69], 2, v151
	s_and_b64 s[70:71], s[72:73], s[70:71]
	v_cmp_gt_i32_e64 s[66:67], 1, v151
	s_and_b64 s[68:69], s[70:71], s[68:69]
	v_cmp_gt_i32_e64 s[64:65], 0, v151
	s_and_b64 s[66:67], s[68:69], s[66:67]
	s_and_b64 s[64:65], s[66:67], s[64:65]
	v_cmp_gt_i32_e64 s[62:63], 58, v151
	v_cndmask_b32_e64 v86, v86, v221, s[64:65]
	v_cmp_gt_i32_e64 s[64:65], 59, v151
	v_cmp_gt_i32_e64 s[60:61], 57, v151
	s_and_b64 s[62:63], s[64:65], s[62:63]
	v_cmp_gt_i32_e64 s[58:59], 56, v151
	s_and_b64 s[60:61], s[62:63], s[60:61]
	v_cmp_gt_i32_e64 s[56:57], 51, v151
	s_and_b64 s[58:59], s[60:61], s[58:59]
	v_cmp_gt_i32_e64 s[54:55], 50, v151
	s_and_b64 s[56:57], s[58:59], s[56:57]
	v_cmp_gt_i32_e64 s[50:51], 49, v151
	s_and_b64 s[54:55], s[56:57], s[54:55]
	v_cmp_gt_i32_e64 s[48:49], 48, v151
	s_and_b64 s[50:51], s[54:55], s[50:51]
	v_cmp_gt_i32_e64 s[46:47], 43, v151
	s_and_b64 s[48:49], s[50:51], s[48:49]
	v_cmp_gt_i32_e64 s[44:45], 42, v151
	s_and_b64 s[46:47], s[48:49], s[46:47]
	v_cmp_gt_i32_e64 s[42:43], 41, v151
	s_and_b64 s[44:45], s[46:47], s[44:45]
	v_cmp_gt_i32_e64 s[40:41], 40, v151
	s_and_b64 s[42:43], s[44:45], s[42:43]
	v_cmp_gt_i32_e64 s[38:39], 35, v151
	s_and_b64 s[40:41], s[42:43], s[40:41]
	v_cmp_gt_i32_e64 s[36:37], 34, v151
	s_and_b64 s[38:39], s[40:41], s[38:39]
	v_cmp_gt_i32_e64 s[0:1], 33, v151
	s_and_b64 s[36:37], s[38:39], s[36:37]
	v_cmp_gt_i32_e32 vcc, 32, v151
	s_and_b64 s[0:1], s[36:37], s[0:1]
	v_cndmask_b32_e64 v88, v88, v221, s[68:69]
	v_readlane_b32 s68, v255, 2
	s_and_b64 vcc, s[0:1], vcc
	v_cndmask_b32_e64 v101, v101, v221, s[96:97]
	v_cndmask_b32_e64 v100, v100, v221, s[94:95]
	v_cndmask_b32_e64 v99, v99, v221, s[92:93]
	v_cndmask_b32_e64 v98, v98, v221, s[90:91]
	v_cndmask_b32_e64 v97, v97, v221, s[88:89]
	v_cndmask_b32_e64 v96, v96, v221, s[86:87]
	v_cndmask_b32_e64 v95, v95, v221, s[84:85]
	v_cndmask_b32_e64 v94, v94, v221, s[80:81]
	v_cndmask_b32_e64 v93, v93, v221, s[78:79]
	v_cndmask_b32_e64 v92, v92, v221, s[76:77]
	v_cndmask_b32_e64 v91, v91, v221, s[74:75]
	v_cndmask_b32_e64 v90, v90, v221, s[72:73]
	s_mov_b32 s72, s18
	v_cndmask_b32_e64 v89, v89, v221, s[70:71]
	v_readlane_b32 s71, v255, 13
	v_readlane_b32 s19, v255, 12
	v_readlane_b32 s70, v255, 11
	v_readlane_b32 s69, v255, 3
	v_cndmask_b32_e64 v87, v87, v221, s[66:67]
	v_cndmask_b32_e64 v79, v79, v221, s[64:65]
	v_cndmask_b32_e64 v78, v78, v221, s[62:63]
	s_mov_b32 s62, s26
	v_cndmask_b32_e64 v77, v77, v221, s[60:61]
	v_cndmask_b32_e64 v76, v76, v221, s[58:59]
	v_cndmask_b32_e64 v75, v75, v221, s[56:57]
	v_cndmask_b32_e64 v74, v74, v221, s[54:55]
	v_cndmask_b32_e64 v73, v73, v221, s[50:51]
	v_cndmask_b32_e64 v72, v72, v221, s[48:49]
	v_cndmask_b32_e64 v71, v71, v221, s[46:47]
	v_cndmask_b32_e64 v70, v70, v221, s[44:45]
	v_cndmask_b32_e64 v69, v69, v221, s[42:43]
	v_cndmask_b32_e64 v68, v68, v221, s[40:41]
	v_cndmask_b32_e64 v67, v67, v221, s[38:39]
	v_cndmask_b32_e64 v66, v66, v221, s[36:37]
	v_cndmask_b32_e64 v65, v65, v221, s[0:1]
	v_cndmask_b32_e32 v64, v64, v221, vcc
